# v20 + bf16 weight-prep stores (P0 and the in-mixer-phase next-layer prep) write-through (sc0 sc1)
# baseline (speedup 1.0000x reference)
.LBB0_53:
	s_waitcnt lgkmcnt(0)
	ds_read2_b32 v[76:77], v55 offset1:8
	ds_read2_b32 v[78:79], v55 offset0:33 offset1:41
	ds_read2_b32 v[80:81], v55 offset0:66 offset1:74
	ds_read2_b32 v[82:83], v55 offset0:99 offset1:107
	v_mov_b32_e32 v43, v33
	v_lshl_add_u64 v[44:45], v[44:45], 0, v[42:43]
	s_waitcnt lgkmcnt(3)
	v_bfe_u32 v32, v76, 16, 1
	v_add3_u32 v32, v76, v32, s33
	s_waitcnt lgkmcnt(2)
	v_bfe_u32 v43, v78, 16, 1
	ds_read2_b32 v[84:85], v55 offset0:132 offset1:140
	v_lshrrev_b32_e32 v32, 16, v32
	v_add3_u32 v43, v78, v43, s33
	ds_read2_b32 v[86:87], v55 offset0:165 offset1:173
	v_and_or_b32 v48, v43, s34, v32
	s_waitcnt lgkmcnt(3)
	v_bfe_u32 v32, v80, 16, 1
	v_add3_u32 v32, v80, v32, s33
	s_waitcnt lgkmcnt(2)
	v_bfe_u32 v43, v82, 16, 1
	ds_read2_b32 v[88:89], v55 offset0:198 offset1:206
	v_lshrrev_b32_e32 v32, 16, v32
	v_add3_u32 v43, v82, v43, s33
	ds_read2_b32 v[90:91], v55 offset0:231 offset1:239
	v_and_or_b32 v49, v43, s34, v32
	s_waitcnt lgkmcnt(3)
	v_bfe_u32 v32, v84, 16, 1
	v_add3_u32 v32, v84, v32, s33
	s_waitcnt lgkmcnt(2)
	v_bfe_u32 v43, v86, 16, 1
	v_lshrrev_b32_e32 v32, 16, v32
	v_add3_u32 v43, v86, v43, s33
	v_and_or_b32 v50, v43, s34, v32
	s_waitcnt lgkmcnt(1)
	v_bfe_u32 v32, v88, 16, 1
	v_add3_u32 v32, v88, v32, s33
	s_waitcnt lgkmcnt(0)
	v_bfe_u32 v43, v90, 16, 1
	v_lshrrev_b32_e32 v32, 16, v32
	v_add3_u32 v43, v90, v43, s33
	v_and_or_b32 v51, v43, s34, v32
	v_bfe_u32 v32, v77, 16, 1
	v_add3_u32 v32, v77, v32, s33
	v_bfe_u32 v43, v79, 16, 1
	v_lshl_add_u64 v[92:93], v[44:45], 0, v[34:35]
	v_lshrrev_b32_e32 v32, 16, v32
	v_add3_u32 v43, v79, v43, s33
	global_store_dwordx4 v[92:93], v[48:51], off sc0 sc1
	ds_read2_b32 v[76:77], v55 offset0:16 offset1:24
	v_lshl_add_u64 v[78:79], v[44:45], 0, v[36:37]
	v_and_or_b32 v48, v43, s34, v32
	v_bfe_u32 v32, v81, 16, 1
	v_add3_u32 v32, v81, v32, s33
	v_bfe_u32 v43, v83, 16, 1
	v_lshrrev_b32_e32 v32, 16, v32
	v_add3_u32 v43, v83, v43, s33
	v_and_or_b32 v49, v43, s34, v32
	v_bfe_u32 v32, v85, 16, 1
	v_add3_u32 v32, v85, v32, s33
	v_bfe_u32 v43, v87, 16, 1
	v_lshrrev_b32_e32 v32, 16, v32
	v_add3_u32 v43, v87, v43, s33
	v_and_or_b32 v50, v43, s34, v32
	v_bfe_u32 v32, v89, 16, 1
	v_add3_u32 v32, v89, v32, s33
	v_bfe_u32 v43, v91, 16, 1
	v_lshrrev_b32_e32 v32, 16, v32
	v_add3_u32 v43, v91, v43, s33
	v_and_or_b32 v51, v43, s34, v32
	global_store_dwordx4 v[78:79], v[48:51], off sc0 sc1
	ds_read2_b32 v[78:79], v55 offset0:49 offset1:57
	ds_read2_b32 v[80:81], v55 offset0:82 offset1:90
	ds_read2_b32 v[82:83], v55 offset0:115 offset1:123
	s_waitcnt lgkmcnt(3)
	v_bfe_u32 v32, v76, 16, 1
	v_add3_u32 v32, v76, v32, s33
	s_waitcnt lgkmcnt(2)
	v_bfe_u32 v43, v78, 16, 1
	ds_read2_b32 v[84:85], v55 offset0:148 offset1:156
	v_lshrrev_b32_e32 v32, 16, v32
	v_add3_u32 v43, v78, v43, s33
	ds_read2_b32 v[86:87], v55 offset0:181 offset1:189
	v_and_or_b32 v48, v43, s34, v32
	s_waitcnt lgkmcnt(3)
	v_bfe_u32 v32, v80, 16, 1
	v_add3_u32 v32, v80, v32, s33
	s_waitcnt lgkmcnt(2)
	v_bfe_u32 v43, v82, 16, 1
	ds_read2_b32 v[88:89], v55 offset0:214 offset1:222
	v_lshrrev_b32_e32 v32, 16, v32
	v_add3_u32 v43, v82, v43, s33
	ds_read2_b32 v[90:91], v55 offset0:247 offset1:255
	v_and_or_b32 v49, v43, s34, v32
	s_waitcnt lgkmcnt(3)
	v_bfe_u32 v32, v84, 16, 1
	v_add3_u32 v32, v84, v32, s33
	s_waitcnt lgkmcnt(2)
	v_bfe_u32 v43, v86, 16, 1
	v_lshrrev_b32_e32 v32, 16, v32
	v_add3_u32 v43, v86, v43, s33
	v_and_or_b32 v50, v43, s34, v32
	s_waitcnt lgkmcnt(1)
	v_bfe_u32 v32, v88, 16, 1
	v_add3_u32 v32, v88, v32, s33
	s_waitcnt lgkmcnt(0)
	v_bfe_u32 v43, v90, 16, 1
	v_lshrrev_b32_e32 v32, 16, v32
	v_add3_u32 v43, v90, v43, s33
	v_and_or_b32 v51, v43, s34, v32
	v_bfe_u32 v32, v77, 16, 1
	v_add3_u32 v32, v77, v32, s33
	v_bfe_u32 v43, v79, 16, 1
	v_lshl_add_u64 v[92:93], v[44:45], 0, v[38:39]
	v_lshrrev_b32_e32 v32, 16, v32
	v_add3_u32 v43, v79, v43, s33
	global_store_dwordx4 v[92:93], v[48:51], off sc0 sc1
	v_lshl_add_u64 v[44:45], v[44:45], 0, v[40:41]
	s_add_i32 s1, s1, s9
	v_and_or_b32 v48, v43, s34, v32
	v_bfe_u32 v32, v81, 16, 1
	v_add3_u32 v32, v81, v32, s33
	v_bfe_u32 v43, v83, 16, 1
	v_lshrrev_b32_e32 v32, 16, v32
	v_add3_u32 v43, v83, v43, s33
	v_and_or_b32 v49, v43, s34, v32
	v_bfe_u32 v32, v85, 16, 1
	v_add3_u32 v32, v85, v32, s33
	v_bfe_u32 v43, v87, 16, 1
	v_lshrrev_b32_e32 v32, 16, v32
	v_add3_u32 v43, v87, v43, s33
	v_and_or_b32 v50, v43, s34, v32
	v_bfe_u32 v32, v89, 16, 1
	v_add3_u32 v32, v89, v32, s33
	v_bfe_u32 v43, v91, 16, 1
	v_lshrrev_b32_e32 v32, 16, v32
	v_add3_u32 v43, v91, v43, s33
	v_and_or_b32 v51, v43, s34, v32
	global_store_dwordx4 v[44:45], v[48:51], off sc0 sc1
	s_waitcnt lgkmcnt(0)
	s_add_i32 s26, s26, s27
	s_cmpk_lt_i32 s35, 0xa80
	v_mov_b64_e32 v[44:45], v[46:47]
	s_cbranch_scc0 .LBB0_97
